# LayerNorm phases: wave sums via DPP + permlane swaps instead of ds_bpermute butterflies (bit-identical)
# speedup vs baseline: 1.0193x; 1.0058x over previous
.LBB0_2013:
	s_or_b64 exec, exec, s[4:5]
	s_waitcnt vmcnt(3)
	v_lshlrev_b32_e32 v67, 16, v59
	v_lshlrev_b32_e32 v66, 16, v58
	v_and_b32_e32 v77, 0xffff0000, v59
	v_and_b32_e32 v76, 0xffff0000, v58
	s_waitcnt vmcnt(2)
	v_lshlrev_b32_e32 v79, 16, v65
	v_lshlrev_b32_e32 v78, 16, v64
	v_and_b32_e32 v65, 0xffff0000, v65
	v_and_b32_e32 v64, 0xffff0000, v64
	v_pk_add_f32 v[58:59], v[66:67], v[76:77]
	v_pk_add_f32 v[80:81], v[78:79], v[64:65]
	v_add_f32_e32 v34, v58, v59
	s_waitcnt vmcnt(1)
	v_lshlrev_b32_e32 v82, 16, v62
	v_and_b32_e32 v83, 0xffff0000, v62
	v_lshlrev_b32_e32 v62, 16, v63
	v_and_b32_e32 v63, 0xffff0000, v63
	s_waitcnt vmcnt(0)
	v_lshlrev_b32_e32 v59, 16, v60
	v_and_b32_e32 v89, 0xffff0000, v60
	v_lshlrev_b32_e32 v85, 16, v61
	v_and_b32_e32 v87, 0xffff0000, v61
	v_pk_add_f32 v[60:61], v[80:81], v[80:81] op_sel:[0,1] op_sel_hi:[1,0]
	v_add_f32_e32 v58, 0, v34
	v_add_f32_e32 v84, v82, v83
	v_add_f32_e32 v86, v62, v63
	v_mov_b32_e32 v61, v89
	v_pk_add_f32 v[60:61], v[58:59], v[60:61]
	v_pk_add_f32 v[80:81], v[84:85], v[86:87]
	v_lshl_add_u64 v[56:57], v[38:39], 0, v[56:57]
	v_pk_add_f32 v[60:61], v[60:61], v[80:81]
	v_lshlrev_b64 v[46:47], 10, v[46:47]
	v_add_f32_e32 v34, v60, v61
	v_lshl_add_u64 v[46:47], v[40:41], 0, v[46:47]
	s_nop 1
	v_add_f32_dpp v34, v34, v34 quad_perm:[1,0,3,2] row_mask:0xf bank_mask:0xf
	s_nop 1
	v_add_f32_dpp v34, v34, v34 quad_perm:[2,3,0,1] row_mask:0xf bank_mask:0xf
	s_nop 1
	v_add_f32_dpp v34, v34, v34 row_half_mirror row_mask:0xf bank_mask:0xf
	s_nop 1
	v_add_f32_dpp v34, v34, v34 row_mirror row_mask:0xf bank_mask:0xf
	v_mov_b32_e32 v58, v34
	v_mov_b32_e32 v100, v34
	s_nop 1
	v_permlane16_swap_b32_e32 v58, v100
	v_add_f32_e32 v34, v58, v100
	v_mov_b32_e32 v58, v34
	v_mov_b32_e32 v100, v34
	s_nop 1
	v_permlane32_swap_b32_e32 v58, v100
	v_add_f32_e32 v58, v58, v100
	v_fmac_f32_e32 v76, 0xba800000, v58
	v_fmac_f32_e32 v77, 0xba800000, v58
	v_fmac_f32_e32 v67, 0xba800000, v58
	v_fmac_f32_e32 v66, 0xba800000, v58
	v_mov_b32_e32 v60, v67
	v_mov_b32_e32 v61, v77
	v_mov_b32_e32 v67, v76
	v_pk_mul_f32 v[80:81], v[60:61], v[60:61]
	v_pk_mul_f32 v[76:77], v[66:67], v[66:67]
	v_fmac_f32_e32 v64, 0xba800000, v58
	v_fmac_f32_e32 v65, 0xba800000, v58
	v_fmac_f32_e32 v79, 0xba800000, v58
	v_pk_mov_b32 v[90:91], v[76:77], v[80:81] op_sel:[1,0]
	v_mov_b32_e32 v77, v81
	v_fmac_f32_e32 v78, 0xba800000, v58
	v_mov_b32_e32 v80, v79
	v_mov_b32_e32 v81, v65
	v_mov_b32_e32 v79, v64
	v_pk_add_f32 v[76:77], v[90:91], v[76:77]
	v_pk_mul_f32 v[90:91], v[80:81], v[80:81]
	v_pk_mul_f32 v[64:65], v[78:79], v[78:79]
	v_fmac_f32_e32 v82, 0xba800000, v58
	v_pk_mov_b32 v[92:93], v[64:65], v[90:91] op_sel:[1,0]
	v_mov_b32_e32 v65, v91
	v_fmac_f32_e32 v83, 0xba800000, v58
	v_fmac_f32_e32 v62, 0xba800000, v58
	v_mul_f32_e32 v34, v82, v82
	v_pk_add_f32 v[64:65], v[92:93], v[64:65]
	v_fmac_f32_e32 v63, 0xba800000, v58
	v_pk_fma_f32 v[90:91], v[82:83], v[82:83], v[34:35] op_sel_hi:[1,1,0]
	v_mul_f32_e32 v34, v62, v62
	v_pk_add_f32 v[76:77], v[76:77], v[76:77] op_sel_hi:[0,1]
	v_pk_add_f32 v[64:65], v[64:65], v[64:65] op_sel_hi:[0,1]
	v_pk_fma_f32 v[92:93], v[62:63], v[62:63], v[34:35] op_sel_hi:[1,1,0]
	v_fmac_f32_e32 v87, 0xba800000, v58
	v_fmac_f32_e32 v85, 0xba800000, v58
	v_fmac_f32_e32 v89, 0xba800000, v58
	v_fmac_f32_e32 v59, 0xba800000, v58
	v_mul_f32_e32 v90, v59, v59
	v_mul_f32_e32 v92, v89, v89
	v_mul_f32_e32 v76, v85, v85
	v_mul_f32_e32 v64, v87, v87
	v_pk_add_f32 v[90:91], v[90:91], v[92:93]
	v_pk_add_f32 v[64:65], v[76:77], v[64:65]
	v_mov_b32_e32 v88, v59
	v_pk_add_f32 v[64:65], v[90:91], v[64:65]
	v_mov_b32_e32 v86, v85
	v_add_f32_e32 v34, v64, v65
	s_nop 1
	v_add_f32_dpp v34, v34, v34 quad_perm:[1,0,3,2] row_mask:0xf bank_mask:0xf
	s_nop 1
	v_add_f32_dpp v34, v34, v34 quad_perm:[2,3,0,1] row_mask:0xf bank_mask:0xf
	s_nop 1
	v_add_f32_dpp v34, v34, v34 row_half_mirror row_mask:0xf bank_mask:0xf
	s_nop 1
	v_add_f32_dpp v34, v34, v34 row_mirror row_mask:0xf bank_mask:0xf
	v_mov_b32_e32 v58, v34
	v_mov_b32_e32 v100, v34
	s_nop 1
	v_permlane16_swap_b32_e32 v58, v100
	v_add_f32_e32 v34, v58, v100
	v_mov_b32_e32 v58, v34
	v_mov_b32_e32 v100, v34
	s_nop 1
	v_permlane32_swap_b32_e32 v58, v100
	v_add_f32_e32 v34, v58, v100
	v_fmamk_f32 v34, v34, 0x3a800000, v33
	v_mul_f32_e32 v58, 0x4f800000, v34
	v_cmp_gt_f32_e32 vcc, s7, v34
	s_nop 1
	v_cndmask_b32_e32 v34, v34, v58, vcc
	v_sqrt_f32_e32 v58, v34
	s_nop 0
	v_add_u32_e32 v64, -1, v58
	v_fma_f32 v65, -v64, v58, v34
	v_cmp_ge_f32_e64 s[42:43], 0, v65
	v_add_u32_e32 v65, 1, v58
	s_nop 0
	v_cndmask_b32_e64 v64, v58, v64, s[42:43]
	v_fma_f32 v58, -v65, v58, v34
	v_cmp_lt_f32_e64 s[42:43], 0, v58
	s_nop 1
	v_cndmask_b32_e64 v58, v64, v65, s[42:43]
	v_mul_f32_e32 v64, 0x37800000, v58
	v_cndmask_b32_e32 v58, v58, v64, vcc
	v_cmp_class_f32_e32 vcc, v34, v74
	s_nop 1
	v_cndmask_b32_e32 v34, v58, v34, vcc
	v_div_scale_f32 v58, s[4:5], v34, v34, 1.0
	v_rcp_f32_e32 v64, v58
	s_nop 0
	v_fma_f32 v65, -v58, v64, 1.0
	v_fmac_f32_e32 v64, v65, v64
	v_div_scale_f32 v65, vcc, 1.0, v34, 1.0
	v_mul_f32_e32 v75, v65, v64
	v_fma_f32 v76, -v58, v75, v65
	v_fmac_f32_e32 v75, v76, v64
	v_fma_f32 v58, -v58, v75, v65
	v_div_fmas_f32 v58, v58, v64, v75
	v_div_fixup_f32 v34, v58, v34, 1.0
	v_pk_mul_f32 v[64:65], v[66:67], v[34:35] op_sel_hi:[1,0]
	v_pk_mul_f32 v[60:61], v[60:61], v[34:35] op_sel_hi:[1,0]
	v_pk_fma_f32 v[64:65], v[0:1], v[64:65], v[4:5]
	v_pk_fma_f32 v[60:61], v[2:3], v[60:61], v[6:7]
	v_cvt_pk_bf16_f32 v66, v64, v65
	v_mul_f32_e32 v58, 0x41800000, v64
	v_mul_f32_e32 v64, 0x41800000, v65
	v_mov_b32_e32 v65, 0
	v_cvt_pk_fp8_f32 v65, v58, v64
	v_cvt_pk_bf16_f32 v67, v60, v61
	v_mul_f32_e32 v58, 0x41800000, v60
	v_mul_f32_e32 v60, 0x41800000, v61
	v_cvt_pk_fp8_f32 v65, v58, v60 op_sel:[0,0,1]
	v_pk_mul_f32 v[60:61], v[78:79], v[34:35] op_sel_hi:[1,0]
	global_store_dwordx2 v[56:57], v[66:67], off
	v_pk_fma_f32 v[60:61], v[8:9], v[60:61], v[12:13]
	v_mov_b32_e32 v67, 0
	v_mul_f32_e32 v58, 0x41800000, v60
	v_mul_f32_e32 v66, 0x41800000, v61
	v_cvt_pk_fp8_f32 v67, v58, v66
	global_store_dword v[46:47], v65, off
	v_pk_mul_f32 v[64:65], v[80:81], v[34:35] op_sel_hi:[1,0]
	v_cvt_pk_bf16_f32 v60, v60, v61
	v_pk_fma_f32 v[64:65], v[10:11], v[64:65], v[14:15]
	v_pk_mul_f32 v[62:63], v[62:63], v[34:35] op_sel_hi:[1,0]
	v_mul_f32_e32 v58, 0x41800000, v64
	v_mul_f32_e32 v66, 0x41800000, v65
	v_cvt_pk_fp8_f32 v67, v58, v66 op_sel:[0,0,1]
	v_cvt_pk_bf16_f32 v61, v64, v65
	global_store_dwordx2 v[56:57], v[60:61], off offset:512
	global_store_dword v[46:47], v67, off offset:256
	v_pk_mul_f32 v[60:61], v[82:83], v[34:35] op_sel_hi:[1,0]
	v_mov_b32_e32 v65, 0
	v_pk_fma_f32 v[60:61], v[16:17], v[60:61], v[20:21]
	v_pk_fma_f32 v[62:63], v[18:19], v[62:63], v[22:23]
	v_mul_f32_e32 v58, 0x41800000, v60
	v_mul_f32_e32 v64, 0x41800000, v61
	v_cvt_pk_fp8_f32 v65, v58, v64
	v_mul_f32_e32 v58, 0x41800000, v62
	v_mul_f32_e32 v64, 0x41800000, v63
	v_cvt_pk_bf16_f32 v60, v60, v61
	v_cvt_pk_fp8_f32 v65, v58, v64 op_sel:[0,0,1]
	v_pk_mul_f32 v[58:59], v[88:89], v[34:35] op_sel_hi:[1,0]
	v_cvt_pk_bf16_f32 v61, v62, v63
	v_pk_fma_f32 v[58:59], v[24:25], v[58:59], v[28:29]
	global_store_dwordx2 v[56:57], v[60:61], off offset:1024
	global_store_dword v[46:47], v65, off offset:512
	v_pk_mul_f32 v[60:61], v[86:87], v[34:35] op_sel_hi:[1,0]
	v_mul_f32_e32 v34, 0x41800000, v58
	v_mul_f32_e32 v62, 0x41800000, v59
	v_mov_b32_e32 v63, 0
	v_cvt_pk_fp8_f32 v63, v34, v62
	v_pk_fma_f32 v[60:61], v[26:27], v[60:61], v[30:31]
	v_cvt_pk_bf16_f32 v58, v58, v59
	v_mul_f32_e32 v34, 0x41800000, v60
	v_mul_f32_e32 v62, 0x41800000, v61
	v_cvt_pk_fp8_f32 v63, v34, v62 op_sel:[0,0,1]
	v_cvt_pk_bf16_f32 v59, v60, v61
	v_cmp_gt_i32_e32 vcc, s6, v42
	global_store_dwordx2 v[56:57], v[58:59], off offset:1536
	global_store_dword v[46:47], v63, off offset:768
	s_and_saveexec_b64 s[4:5], vcc
	s_cbranch_execz .LBB0_2004
	v_lshlrev_b32_e32 v47, 16, v49
	v_lshlrev_b32_e32 v46, 16, v48
	v_and_b32_e32 v49, 0xffff0000, v49
	v_and_b32_e32 v48, 0xffff0000, v48
	v_lshlrev_b32_e32 v59, 16, v53
	v_lshlrev_b32_e32 v58, 16, v52
	v_and_b32_e32 v53, 0xffff0000, v53
	v_and_b32_e32 v52, 0xffff0000, v52
	v_pk_add_f32 v[56:57], v[46:47], v[48:49]
	v_pk_add_f32 v[60:61], v[58:59], v[52:53]
	v_add_f32_e32 v34, v56, v57
	v_lshlrev_b32_e32 v62, 16, v50
	v_and_b32_e32 v63, 0xffff0000, v50
	v_lshlrev_b32_e32 v50, 16, v51
	v_and_b32_e32 v51, 0xffff0000, v51
	v_lshlrev_b32_e32 v57, 16, v54
	v_and_b32_e32 v77, 0xffff0000, v54
	v_lshlrev_b32_e32 v65, 16, v55
	v_and_b32_e32 v67, 0xffff0000, v55
	v_pk_add_f32 v[54:55], v[60:61], v[60:61] op_sel:[0,1] op_sel_hi:[1,0]
	v_add_f32_e32 v56, 0, v34
	v_add_f32_e32 v64, v62, v63
	v_add_f32_e32 v66, v50, v51
	v_mov_b32_e32 v55, v77
	v_pk_add_f32 v[54:55], v[56:57], v[54:55]
	v_pk_add_f32 v[60:61], v[64:65], v[66:67]
	v_lshl_add_u64 v[44:45], v[38:39], 0, v[44:45]
	v_pk_add_f32 v[54:55], v[54:55], v[60:61]
	s_nop 0
	v_add_f32_e32 v34, v54, v55
	s_nop 1
	v_add_f32_dpp v34, v34, v34 quad_perm:[1,0,3,2] row_mask:0xf bank_mask:0xf
	s_nop 1
	v_add_f32_dpp v34, v34, v34 quad_perm:[2,3,0,1] row_mask:0xf bank_mask:0xf
	s_nop 1
	v_add_f32_dpp v34, v34, v34 row_half_mirror row_mask:0xf bank_mask:0xf
	s_nop 1
	v_add_f32_dpp v34, v34, v34 row_mirror row_mask:0xf bank_mask:0xf
	v_mov_b32_e32 v54, v34
	v_mov_b32_e32 v100, v34
	s_nop 1
	v_permlane16_swap_b32_e32 v54, v100
	v_add_f32_e32 v34, v54, v100
	v_mov_b32_e32 v54, v34
	v_mov_b32_e32 v100, v34
	s_nop 1
	v_permlane32_swap_b32_e32 v54, v100
	v_add_f32_e32 v56, v54, v100
	v_fmac_f32_e32 v48, 0xba800000, v56
	v_fmac_f32_e32 v49, 0xba800000, v56
	v_fmac_f32_e32 v47, 0xba800000, v56
	v_fmac_f32_e32 v46, 0xba800000, v56
	v_mov_b32_e32 v54, v47
	v_mov_b32_e32 v55, v49
	v_mov_b32_e32 v47, v48
	v_pk_mul_f32 v[60:61], v[54:55], v[54:55]
	v_pk_mul_f32 v[48:49], v[46:47], v[46:47]
	v_fmac_f32_e32 v52, 0xba800000, v56
	v_fmac_f32_e32 v53, 0xba800000, v56
	v_fmac_f32_e32 v59, 0xba800000, v56
	v_pk_mov_b32 v[78:79], v[48:49], v[60:61] op_sel:[1,0]
	v_mov_b32_e32 v49, v61
	v_fmac_f32_e32 v58, 0xba800000, v56
	v_mov_b32_e32 v60, v59
	v_mov_b32_e32 v61, v53
	v_mov_b32_e32 v59, v52
	v_pk_add_f32 v[48:49], v[78:79], v[48:49]
	v_pk_mul_f32 v[78:79], v[60:61], v[60:61]
	v_pk_mul_f32 v[52:53], v[58:59], v[58:59]
	v_fmac_f32_e32 v62, 0xba800000, v56
	v_pk_mov_b32 v[80:81], v[52:53], v[78:79] op_sel:[1,0]
	v_mov_b32_e32 v53, v79
	v_fmac_f32_e32 v63, 0xba800000, v56
	v_fmac_f32_e32 v50, 0xba800000, v56
	v_mul_f32_e32 v34, v62, v62
	v_pk_add_f32 v[52:53], v[80:81], v[52:53]
	v_fmac_f32_e32 v51, 0xba800000, v56
	v_pk_fma_f32 v[78:79], v[62:63], v[62:63], v[34:35] op_sel_hi:[1,1,0]
	v_mul_f32_e32 v34, v50, v50
	v_pk_add_f32 v[48:49], v[48:49], v[48:49] op_sel_hi:[0,1]
	v_pk_add_f32 v[52:53], v[52:53], v[52:53] op_sel_hi:[0,1]
	v_pk_fma_f32 v[80:81], v[50:51], v[50:51], v[34:35] op_sel_hi:[1,1,0]
	v_fmac_f32_e32 v67, 0xba800000, v56
	v_fmac_f32_e32 v65, 0xba800000, v56
	v_fmac_f32_e32 v77, 0xba800000, v56
	v_fmac_f32_e32 v57, 0xba800000, v56
	v_mul_f32_e32 v78, v57, v57
	v_mul_f32_e32 v80, v77, v77
	v_mul_f32_e32 v48, v65, v65
	v_mul_f32_e32 v52, v67, v67
	v_pk_add_f32 v[78:79], v[78:79], v[80:81]
	v_pk_add_f32 v[48:49], v[48:49], v[52:53]
	v_mov_b32_e32 v76, v57
	v_pk_add_f32 v[48:49], v[78:79], v[48:49]
	v_mov_b32_e32 v66, v65
	v_add_f32_e32 v34, v48, v49
	s_nop 1
	v_add_f32_dpp v34, v34, v34 quad_perm:[1,0,3,2] row_mask:0xf bank_mask:0xf
	s_nop 1
	v_add_f32_dpp v34, v34, v34 quad_perm:[2,3,0,1] row_mask:0xf bank_mask:0xf
	s_nop 1
	v_add_f32_dpp v34, v34, v34 row_half_mirror row_mask:0xf bank_mask:0xf
	s_nop 1
	v_add_f32_dpp v34, v34, v34 row_mirror row_mask:0xf bank_mask:0xf
	v_mov_b32_e32 v48, v34
	v_mov_b32_e32 v100, v34
	s_nop 1
	v_permlane16_swap_b32_e32 v48, v100
	v_add_f32_e32 v34, v48, v100
	v_mov_b32_e32 v48, v34
	v_mov_b32_e32 v100, v34
	s_nop 1
	v_permlane32_swap_b32_e32 v48, v100
	v_add_f32_e32 v34, v48, v100
	v_fmamk_f32 v34, v34, 0x3a800000, v33
	v_mul_f32_e32 v48, 0x4f800000, v34
	v_cmp_gt_f32_e32 vcc, s7, v34
	s_nop 1
	v_cndmask_b32_e32 v34, v34, v48, vcc
	v_sqrt_f32_e32 v48, v34
	s_nop 0
	v_add_u32_e32 v49, -1, v48
	v_fma_f32 v52, -v49, v48, v34
	v_cmp_ge_f32_e64 s[42:43], 0, v52
	v_add_u32_e32 v52, 1, v48
	s_nop 0
	v_cndmask_b32_e64 v49, v48, v49, s[42:43]
	v_fma_f32 v48, -v52, v48, v34
	v_cmp_lt_f32_e64 s[42:43], 0, v48
	s_nop 1
	v_cndmask_b32_e64 v48, v49, v52, s[42:43]
	v_mul_f32_e32 v49, 0x37800000, v48
	v_cndmask_b32_e32 v48, v48, v49, vcc
	v_cmp_class_f32_e32 vcc, v34, v74
	s_nop 1
	v_cndmask_b32_e32 v34, v48, v34, vcc
	v_div_scale_f32 v48, s[8:9], v34, v34, 1.0
	v_rcp_f32_e32 v49, v48
	s_nop 0
	v_fma_f32 v52, -v48, v49, 1.0
	v_fmac_f32_e32 v49, v52, v49
	v_div_scale_f32 v52, vcc, 1.0, v34, 1.0
	v_mul_f32_e32 v53, v52, v49
	v_fma_f32 v56, -v48, v53, v52
	v_fmac_f32_e32 v53, v56, v49
	v_fma_f32 v48, -v48, v53, v52
	v_div_fmas_f32 v48, v48, v49, v53
	v_div_fixup_f32 v34, v48, v34, 1.0
	v_pk_mul_f32 v[46:47], v[46:47], v[34:35] op_sel_hi:[1,0]
	v_lshlrev_b64 v[48:49], 10, v[42:43]
	v_pk_fma_f32 v[46:47], v[0:1], v[46:47], v[4:5]
	v_pk_mul_f32 v[52:53], v[54:55], v[34:35] op_sel_hi:[1,0]
	v_cvt_pk_bf16_f32 v54, v46, v47
	v_mul_f32_e32 v43, 0x41800000, v46
	v_mul_f32_e32 v46, 0x41800000, v47
	v_mov_b32_e32 v56, v35
	v_cvt_pk_fp8_f32 v56, v43, v46
	v_pk_fma_f32 v[52:53], v[2:3], v[52:53], v[6:7]
	v_pk_mul_f32 v[50:51], v[50:51], v[34:35] op_sel_hi:[1,0]
	v_mul_f32_e32 v43, 0x41800000, v52
	v_mul_f32_e32 v46, 0x41800000, v53
	v_cvt_pk_fp8_f32 v56, v43, v46 op_sel:[0,0,1]
	v_lshl_add_u64 v[46:47], v[40:41], 0, v[48:49]
	v_pk_mul_f32 v[48:49], v[58:59], v[34:35] op_sel_hi:[1,0]
	v_cvt_pk_bf16_f32 v55, v52, v53
	v_pk_fma_f32 v[48:49], v[8:9], v[48:49], v[12:13]
	global_store_dwordx2 v[44:45], v[54:55], off
	v_mul_f32_e32 v43, 0x41800000, v48
	v_mul_f32_e32 v54, 0x41800000, v49
	v_mov_b32_e32 v55, v35
	v_cvt_pk_fp8_f32 v55, v43, v54
	v_pk_mul_f32 v[52:53], v[60:61], v[34:35] op_sel_hi:[1,0]
	v_cvt_pk_bf16_f32 v48, v48, v49
	v_pk_fma_f32 v[52:53], v[10:11], v[52:53], v[14:15]
	global_store_dword v[46:47], v56, off
	v_mul_f32_e32 v43, 0x41800000, v52
	v_mul_f32_e32 v54, 0x41800000, v53
	v_cvt_pk_fp8_f32 v55, v43, v54 op_sel:[0,0,1]
	v_cvt_pk_bf16_f32 v49, v52, v53
	global_store_dwordx2 v[44:45], v[48:49], off offset:512
	global_store_dword v[46:47], v55, off offset:256
	v_pk_mul_f32 v[48:49], v[62:63], v[34:35] op_sel_hi:[1,0]
	v_mov_b32_e32 v53, v35
	v_pk_fma_f32 v[48:49], v[16:17], v[48:49], v[20:21]
	v_pk_fma_f32 v[50:51], v[18:19], v[50:51], v[22:23]
	v_mul_f32_e32 v43, 0x41800000, v48
	v_mul_f32_e32 v52, 0x41800000, v49
	v_cvt_pk_fp8_f32 v53, v43, v52
	v_mul_f32_e32 v43, 0x41800000, v50
	v_mul_f32_e32 v52, 0x41800000, v51
	v_cvt_pk_bf16_f32 v48, v48, v49
	v_cvt_pk_fp8_f32 v53, v43, v52 op_sel:[0,0,1]
	v_cvt_pk_bf16_f32 v49, v50, v51
	global_store_dwordx2 v[44:45], v[48:49], off offset:1024
	global_store_dword v[46:47], v53, off offset:512
	v_pk_mul_f32 v[48:49], v[76:77], v[34:35] op_sel_hi:[1,0]
	v_pk_mul_f32 v[50:51], v[66:67], v[34:35] op_sel_hi:[1,0]
	v_pk_fma_f32 v[48:49], v[24:25], v[48:49], v[28:29]
	v_mov_b32_e32 v52, v35
	v_mul_f32_e32 v34, 0x41800000, v48
	v_mul_f32_e32 v43, 0x41800000, v49
	v_cvt_pk_fp8_f32 v52, v34, v43
	v_pk_fma_f32 v[50:51], v[26:27], v[50:51], v[30:31]
	v_cvt_pk_bf16_f32 v48, v48, v49
	v_mul_f32_e32 v34, 0x41800000, v50
	v_mul_f32_e32 v43, 0x41800000, v51
	v_cvt_pk_fp8_f32 v52, v34, v43 op_sel:[0,0,1]
	v_cvt_pk_bf16_f32 v49, v50, v51
	global_store_dwordx2 v[44:45], v[48:49], off offset:1536
	global_store_dword v[46:47], v52, off offset:768
	s_branch .LBB0_2004

.LBB0_2266:
	s_or_b64 exec, exec, s[0:1]
	s_waitcnt vmcnt(3)
	v_lshlrev_b32_e32 v61, 16, v59
	v_lshlrev_b32_e32 v60, 16, v58
	v_and_b32_e32 v59, 0xffff0000, v59
	v_and_b32_e32 v58, 0xffff0000, v58
	s_waitcnt vmcnt(2)
	v_lshlrev_b32_e32 v73, 16, v57
	v_lshlrev_b32_e32 v72, 16, v56
	v_and_b32_e32 v57, 0xffff0000, v57
	v_and_b32_e32 v56, 0xffff0000, v56
	v_pk_add_f32 v[70:71], v[60:61], v[58:59]
	v_pk_add_f32 v[74:75], v[72:73], v[56:57]
	v_add_f32_e32 v34, v70, v71
	s_waitcnt vmcnt(1)
	v_lshlrev_b32_e32 v76, 16, v54
	v_and_b32_e32 v77, 0xffff0000, v54
	v_lshlrev_b32_e32 v78, 16, v55
	v_and_b32_e32 v79, 0xffff0000, v55
	s_waitcnt vmcnt(0)
	v_lshlrev_b32_e32 v71, 16, v52
	v_and_b32_e32 v85, 0xffff0000, v52
	v_lshlrev_b32_e32 v81, 16, v53
	v_and_b32_e32 v83, 0xffff0000, v53
	v_pk_add_f32 v[52:53], v[74:75], v[74:75] op_sel:[0,1] op_sel_hi:[1,0]
	v_add_f32_e32 v70, 0, v34
	v_add_f32_e32 v80, v76, v77
	v_add_f32_e32 v82, v78, v79
	v_mov_b32_e32 v53, v85
	v_pk_add_f32 v[52:53], v[70:71], v[52:53]
	v_pk_add_f32 v[54:55], v[80:81], v[82:83]
	v_lshlrev_b64 v[42:43], 12, v[42:43]
	v_pk_add_f32 v[52:53], v[52:53], v[54:55]
	v_lshl_add_u64 v[42:43], v[38:39], 0, v[42:43]
	v_add_f32_e32 v34, v52, v53
	s_nop 1
	v_add_f32_dpp v34, v34, v34 quad_perm:[1,0,3,2] row_mask:0xf bank_mask:0xf
	s_nop 1
	v_add_f32_dpp v34, v34, v34 quad_perm:[2,3,0,1] row_mask:0xf bank_mask:0xf
	s_nop 1
	v_add_f32_dpp v34, v34, v34 row_half_mirror row_mask:0xf bank_mask:0xf
	s_nop 1
	v_add_f32_dpp v34, v34, v34 row_mirror row_mask:0xf bank_mask:0xf
	v_mov_b32_e32 v52, v34
	v_mov_b32_e32 v100, v34
	s_nop 1
	v_permlane16_swap_b32_e32 v52, v100
	v_add_f32_e32 v34, v52, v100
	v_mov_b32_e32 v52, v34
	v_mov_b32_e32 v100, v34
	s_nop 1
	v_permlane32_swap_b32_e32 v52, v100
	v_add_f32_e32 v69, v52, v100
	v_fmac_f32_e32 v58, 0xba800000, v69
	v_fmac_f32_e32 v59, 0xba800000, v69
	v_fmac_f32_e32 v61, 0xba800000, v69
	v_fmac_f32_e32 v60, 0xba800000, v69
	v_mov_b32_e32 v52, v61
	v_mov_b32_e32 v53, v59
	v_mov_b32_e32 v61, v58
	v_pk_mul_f32 v[54:55], v[52:53], v[52:53]
	v_pk_mul_f32 v[58:59], v[60:61], v[60:61]
	v_fmac_f32_e32 v56, 0xba800000, v69
	v_pk_mov_b32 v[74:75], v[58:59], v[54:55] op_sel:[1,0]
	v_mov_b32_e32 v59, v55
	v_fmac_f32_e32 v57, 0xba800000, v69
	v_fmac_f32_e32 v73, 0xba800000, v69
	v_pk_add_f32 v[54:55], v[74:75], v[58:59]
	v_fmac_f32_e32 v72, 0xba800000, v69
	v_mov_b32_e32 v58, v73
	v_mov_b32_e32 v59, v57
	v_mov_b32_e32 v73, v56
	v_pk_mul_f32 v[74:75], v[58:59], v[58:59]
	v_pk_mul_f32 v[56:57], v[72:73], v[72:73]
	v_fmac_f32_e32 v76, 0xba800000, v69
	v_pk_mov_b32 v[86:87], v[56:57], v[74:75] op_sel:[1,0]
	v_mov_b32_e32 v57, v75
	v_fmac_f32_e32 v77, 0xba800000, v69
	v_fmac_f32_e32 v78, 0xba800000, v69
	v_mul_f32_e32 v34, v76, v76
	v_pk_add_f32 v[56:57], v[86:87], v[56:57]
	v_fmac_f32_e32 v79, 0xba800000, v69
	v_pk_fma_f32 v[74:75], v[76:77], v[76:77], v[34:35] op_sel_hi:[1,1,0]
	v_mul_f32_e32 v34, v78, v78
	v_pk_add_f32 v[54:55], v[54:55], v[54:55] op_sel_hi:[0,1]
	v_pk_add_f32 v[56:57], v[56:57], v[56:57] op_sel_hi:[0,1]
	v_pk_fma_f32 v[86:87], v[78:79], v[78:79], v[34:35] op_sel_hi:[1,1,0]
	v_fmac_f32_e32 v83, 0xba800000, v69
	v_fmac_f32_e32 v81, 0xba800000, v69
	v_fmac_f32_e32 v85, 0xba800000, v69
	v_fmac_f32_e32 v71, 0xba800000, v69
	v_mul_f32_e32 v74, v71, v71
	v_mul_f32_e32 v86, v85, v85
	v_mul_f32_e32 v54, v81, v81
	v_mul_f32_e32 v56, v83, v83
	v_pk_add_f32 v[74:75], v[74:75], v[86:87]
	v_pk_add_f32 v[54:55], v[54:55], v[56:57]
	v_mov_b32_e32 v84, v71
	v_pk_add_f32 v[54:55], v[74:75], v[54:55]
	v_mov_b32_e32 v82, v81
	v_add_f32_e32 v34, v54, v55
	s_nop 1
	v_add_f32_dpp v34, v34, v34 quad_perm:[1,0,3,2] row_mask:0xf bank_mask:0xf
	s_nop 1
	v_add_f32_dpp v34, v34, v34 quad_perm:[2,3,0,1] row_mask:0xf bank_mask:0xf
	s_nop 1
	v_add_f32_dpp v34, v34, v34 row_half_mirror row_mask:0xf bank_mask:0xf
	s_nop 1
	v_add_f32_dpp v34, v34, v34 row_mirror row_mask:0xf bank_mask:0xf
	v_mov_b32_e32 v54, v34
	v_mov_b32_e32 v100, v34
	s_nop 1
	v_permlane16_swap_b32_e32 v54, v100
	v_add_f32_e32 v34, v54, v100
	v_mov_b32_e32 v54, v34
	v_mov_b32_e32 v100, v34
	s_nop 1
	v_permlane32_swap_b32_e32 v54, v100
	v_add_f32_e32 v34, v54, v100
	v_fmamk_f32 v34, v34, 0x3a800000, v67
	v_mul_f32_e32 v54, 0x4f800000, v34
	v_cmp_gt_f32_e32 vcc, s8, v34
	s_nop 1
	v_cndmask_b32_e32 v34, v34, v54, vcc
	v_sqrt_f32_e32 v54, v34
	s_nop 0
	v_add_u32_e32 v55, -1, v54
	v_fma_f32 v56, -v55, v54, v34
	v_cmp_ge_f32_e64 s[0:1], 0, v56
	v_add_u32_e32 v56, 1, v54
	s_nop 0
	v_cndmask_b32_e64 v55, v54, v55, s[0:1]
	v_fma_f32 v54, -v56, v54, v34
	v_cmp_lt_f32_e64 s[0:1], 0, v54
	s_nop 1
	v_cndmask_b32_e64 v54, v55, v56, s[0:1]
	v_mul_f32_e32 v55, 0x37800000, v54
	v_cndmask_b32_e32 v54, v54, v55, vcc
	v_cmp_class_f32_e32 vcc, v34, v68
	s_nop 1
	v_cndmask_b32_e32 v34, v54, v34, vcc
	v_div_scale_f32 v54, s[0:1], v34, v34, 1.0
	v_rcp_f32_e32 v55, v54
	s_nop 0
	v_fma_f32 v56, -v54, v55, 1.0
	v_fmac_f32_e32 v55, v56, v55
	v_div_scale_f32 v56, vcc, 1.0, v34, 1.0
	v_mul_f32_e32 v57, v56, v55
	v_fma_f32 v69, -v54, v57, v56
	v_fmac_f32_e32 v57, v69, v55
	v_fma_f32 v54, -v54, v57, v56
	v_div_fmas_f32 v54, v54, v55, v57
	v_div_fixup_f32 v34, v54, v34, 1.0
	v_pk_mul_f32 v[56:57], v[60:61], v[34:35] op_sel_hi:[1,0]
	v_pk_mul_f32 v[52:53], v[52:53], v[34:35] op_sel_hi:[1,0]
	v_cmp_gt_i32_e32 vcc, s12, v40
	v_pk_fma_f32 v[54:55], v[2:3], v[52:53], v[6:7]
	v_pk_fma_f32 v[52:53], v[0:1], v[56:57], v[4:5]
	global_store_dwordx4 v[42:43], v[52:55], off
	s_nop 1
	v_pk_mul_f32 v[52:53], v[72:73], v[34:35] op_sel_hi:[1,0]
	v_pk_mul_f32 v[54:55], v[58:59], v[34:35] op_sel_hi:[1,0]
	v_pk_fma_f32 v[52:53], v[8:9], v[52:53], v[12:13]
	v_pk_fma_f32 v[54:55], v[10:11], v[54:55], v[14:15]
	global_store_dwordx4 v[42:43], v[52:55], off offset:1024
	s_nop 1
	v_pk_mul_f32 v[52:53], v[76:77], v[34:35] op_sel_hi:[1,0]
	v_pk_mul_f32 v[54:55], v[78:79], v[34:35] op_sel_hi:[1,0]
	v_pk_fma_f32 v[52:53], v[16:17], v[52:53], v[20:21]
	v_pk_fma_f32 v[54:55], v[18:19], v[54:55], v[22:23]
	global_store_dwordx4 v[42:43], v[52:55], off offset:2048
	s_nop 1
	v_pk_mul_f32 v[52:53], v[84:85], v[34:35] op_sel_hi:[1,0]
	v_pk_mul_f32 v[54:55], v[82:83], v[34:35] op_sel_hi:[1,0]
	v_pk_fma_f32 v[52:53], v[24:25], v[52:53], v[28:29]
	v_pk_fma_f32 v[54:55], v[26:27], v[54:55], v[30:31]
	global_store_dwordx4 v[42:43], v[52:55], off offset:3072
	s_and_saveexec_b64 s[6:7], vcc
	s_cbranch_execz .LBB0_2257
	v_lshlrev_b32_e32 v43, 16, v45
	v_lshlrev_b32_e32 v42, 16, v44
	v_and_b32_e32 v45, 0xffff0000, v45
	v_and_b32_e32 v44, 0xffff0000, v44
	v_lshlrev_b32_e32 v55, 16, v49
	v_lshlrev_b32_e32 v54, 16, v48
	v_and_b32_e32 v49, 0xffff0000, v49
	v_and_b32_e32 v48, 0xffff0000, v48
	v_pk_add_f32 v[52:53], v[42:43], v[44:45]
	v_pk_add_f32 v[56:57], v[54:55], v[48:49]
	v_add_f32_e32 v34, v52, v53
	v_lshlrev_b32_e32 v58, 16, v46
	v_and_b32_e32 v59, 0xffff0000, v46
	v_lshlrev_b32_e32 v46, 16, v47
	v_and_b32_e32 v47, 0xffff0000, v47
	v_lshlrev_b32_e32 v53, 16, v50
	v_and_b32_e32 v73, 0xffff0000, v50
	v_lshlrev_b32_e32 v61, 16, v51
	v_and_b32_e32 v71, 0xffff0000, v51
	v_pk_add_f32 v[50:51], v[56:57], v[56:57] op_sel:[0,1] op_sel_hi:[1,0]
	v_add_f32_e32 v52, 0, v34
	v_add_f32_e32 v60, v58, v59
	v_add_f32_e32 v70, v46, v47
	v_mov_b32_e32 v51, v73
	v_pk_add_f32 v[50:51], v[52:53], v[50:51]
	v_pk_add_f32 v[56:57], v[60:61], v[70:71]
	s_nop 0
	v_pk_add_f32 v[50:51], v[50:51], v[56:57]
	s_nop 0
	v_add_f32_e32 v34, v50, v51
	s_nop 1
	v_add_f32_dpp v34, v34, v34 quad_perm:[1,0,3,2] row_mask:0xf bank_mask:0xf
	s_nop 1
	v_add_f32_dpp v34, v34, v34 quad_perm:[2,3,0,1] row_mask:0xf bank_mask:0xf
	s_nop 1
	v_add_f32_dpp v34, v34, v34 row_half_mirror row_mask:0xf bank_mask:0xf
	s_nop 1
	v_add_f32_dpp v34, v34, v34 row_mirror row_mask:0xf bank_mask:0xf
	v_mov_b32_e32 v50, v34
	v_mov_b32_e32 v100, v34
	s_nop 1
	v_permlane16_swap_b32_e32 v50, v100
	v_add_f32_e32 v34, v50, v100
	v_mov_b32_e32 v50, v34
	v_mov_b32_e32 v100, v34
	s_nop 1
	v_permlane32_swap_b32_e32 v50, v100
	v_add_f32_e32 v52, v50, v100
	v_fmac_f32_e32 v44, 0xba800000, v52
	v_fmac_f32_e32 v45, 0xba800000, v52
	v_fmac_f32_e32 v43, 0xba800000, v52
	v_fmac_f32_e32 v42, 0xba800000, v52
	v_mov_b32_e32 v50, v43
	v_mov_b32_e32 v51, v45
	v_mov_b32_e32 v43, v44
	v_pk_mul_f32 v[56:57], v[50:51], v[50:51]
	v_pk_mul_f32 v[44:45], v[42:43], v[42:43]
	v_fmac_f32_e32 v48, 0xba800000, v52
	v_fmac_f32_e32 v49, 0xba800000, v52
	v_fmac_f32_e32 v55, 0xba800000, v52
	v_pk_mov_b32 v[74:75], v[44:45], v[56:57] op_sel:[1,0]
	v_mov_b32_e32 v45, v57
	v_fmac_f32_e32 v54, 0xba800000, v52
	v_mov_b32_e32 v56, v55
	v_mov_b32_e32 v57, v49
	v_mov_b32_e32 v55, v48
	v_pk_add_f32 v[44:45], v[74:75], v[44:45]
	v_pk_mul_f32 v[74:75], v[56:57], v[56:57]
	v_pk_mul_f32 v[48:49], v[54:55], v[54:55]
	v_fmac_f32_e32 v58, 0xba800000, v52
	v_pk_mov_b32 v[76:77], v[48:49], v[74:75] op_sel:[1,0]
	v_mov_b32_e32 v49, v75
	v_fmac_f32_e32 v59, 0xba800000, v52
	v_fmac_f32_e32 v46, 0xba800000, v52
	v_mul_f32_e32 v34, v58, v58
	v_pk_add_f32 v[48:49], v[76:77], v[48:49]
	v_fmac_f32_e32 v47, 0xba800000, v52
	v_pk_fma_f32 v[74:75], v[58:59], v[58:59], v[34:35] op_sel_hi:[1,1,0]
	v_mul_f32_e32 v34, v46, v46
	v_pk_add_f32 v[44:45], v[44:45], v[44:45] op_sel_hi:[0,1]
	v_pk_add_f32 v[48:49], v[48:49], v[48:49] op_sel_hi:[0,1]
	v_pk_fma_f32 v[76:77], v[46:47], v[46:47], v[34:35] op_sel_hi:[1,1,0]
	v_fmac_f32_e32 v71, 0xba800000, v52
	v_fmac_f32_e32 v61, 0xba800000, v52
	v_fmac_f32_e32 v73, 0xba800000, v52
	v_fmac_f32_e32 v53, 0xba800000, v52
	v_mul_f32_e32 v74, v53, v53
	v_mul_f32_e32 v76, v73, v73
	v_mul_f32_e32 v44, v61, v61
	v_mul_f32_e32 v48, v71, v71
	v_pk_add_f32 v[74:75], v[74:75], v[76:77]
	v_pk_add_f32 v[44:45], v[44:45], v[48:49]
	v_mov_b32_e32 v72, v53
	v_pk_add_f32 v[44:45], v[74:75], v[44:45]
	v_mov_b32_e32 v70, v61
	v_add_f32_e32 v34, v44, v45
	s_nop 1
	v_add_f32_dpp v34, v34, v34 quad_perm:[1,0,3,2] row_mask:0xf bank_mask:0xf
	s_nop 1
	v_add_f32_dpp v34, v34, v34 quad_perm:[2,3,0,1] row_mask:0xf bank_mask:0xf
	s_nop 1
	v_add_f32_dpp v34, v34, v34 row_half_mirror row_mask:0xf bank_mask:0xf
	s_nop 1
	v_add_f32_dpp v34, v34, v34 row_mirror row_mask:0xf bank_mask:0xf
	v_mov_b32_e32 v44, v34
	v_mov_b32_e32 v100, v34
	s_nop 1
	v_permlane16_swap_b32_e32 v44, v100
	v_add_f32_e32 v34, v44, v100
	v_mov_b32_e32 v44, v34
	v_mov_b32_e32 v100, v34
	s_nop 1
	v_permlane32_swap_b32_e32 v44, v100
	v_add_f32_e32 v34, v44, v100
	v_fmamk_f32 v34, v34, 0x3a800000, v67
	v_mul_f32_e32 v44, 0x4f800000, v34
	v_cmp_gt_f32_e32 vcc, s8, v34
	s_nop 1
	v_cndmask_b32_e32 v34, v34, v44, vcc
	v_sqrt_f32_e32 v44, v34
	s_nop 0
	v_add_u32_e32 v45, -1, v44
	v_fma_f32 v48, -v45, v44, v34
	v_cmp_ge_f32_e64 s[0:1], 0, v48
	v_add_u32_e32 v48, 1, v44
	s_nop 0
	v_cndmask_b32_e64 v45, v44, v45, s[0:1]
	v_fma_f32 v44, -v48, v44, v34
	v_cmp_lt_f32_e64 s[0:1], 0, v44
	s_nop 1
	v_cndmask_b32_e64 v44, v45, v48, s[0:1]
	v_mul_f32_e32 v45, 0x37800000, v44
	v_cndmask_b32_e32 v44, v44, v45, vcc
	v_cmp_class_f32_e32 vcc, v34, v68
	s_nop 1
	v_cndmask_b32_e32 v34, v44, v34, vcc
	v_div_scale_f32 v44, s[0:1], v34, v34, 1.0
	v_rcp_f32_e32 v45, v44
	s_nop 0
	v_fma_f32 v48, -v44, v45, 1.0
	v_fmac_f32_e32 v45, v48, v45
	v_div_scale_f32 v48, vcc, 1.0, v34, 1.0
	v_mul_f32_e32 v49, v48, v45
	v_fma_f32 v52, -v44, v49, v48
	v_fmac_f32_e32 v49, v52, v45
	v_fma_f32 v44, -v44, v49, v48
	v_div_fmas_f32 v44, v44, v45, v49
	v_div_fixup_f32 v34, v44, v34, 1.0
	v_lshlrev_b64 v[48:49], 12, v[40:41]
	v_pk_mul_f32 v[42:43], v[42:43], v[34:35] op_sel_hi:[1,0]
	v_pk_mul_f32 v[44:45], v[50:51], v[34:35] op_sel_hi:[1,0]
	v_pk_fma_f32 v[42:43], v[0:1], v[42:43], v[4:5]
	v_pk_fma_f32 v[44:45], v[2:3], v[44:45], v[6:7]
	v_lshl_add_u64 v[48:49], v[38:39], 0, v[48:49]
	global_store_dwordx4 v[48:49], v[42:45], off
	s_nop 1
	v_pk_mul_f32 v[42:43], v[54:55], v[34:35] op_sel_hi:[1,0]
	v_pk_mul_f32 v[44:45], v[56:57], v[34:35] op_sel_hi:[1,0]
	v_pk_fma_f32 v[42:43], v[8:9], v[42:43], v[12:13]
	v_pk_fma_f32 v[44:45], v[10:11], v[44:45], v[14:15]
	global_store_dwordx4 v[48:49], v[42:45], off offset:1024
	s_nop 1
	v_pk_mul_f32 v[42:43], v[58:59], v[34:35] op_sel_hi:[1,0]
	v_pk_mul_f32 v[44:45], v[46:47], v[34:35] op_sel_hi:[1,0]
	v_pk_fma_f32 v[42:43], v[16:17], v[42:43], v[20:21]
	v_pk_fma_f32 v[44:45], v[18:19], v[44:45], v[22:23]
	global_store_dwordx4 v[48:49], v[42:45], off offset:2048
	s_nop 1
	v_pk_mul_f32 v[42:43], v[72:73], v[34:35] op_sel_hi:[1,0]
	v_pk_mul_f32 v[44:45], v[70:71], v[34:35] op_sel_hi:[1,0]
	v_pk_fma_f32 v[42:43], v[24:25], v[42:43], v[28:29]
	v_pk_fma_f32 v[44:45], v[26:27], v[44:45], v[30:31]
	global_store_dwordx4 v[48:49], v[42:45], off offset:3072
	s_branch .LBB0_2257
